# attention masked tiles: straight-line mask code for window tiles (compare pairs) and neighbourhood tiles (all 16 bias reads up front, masks applied in sequence) replacing the per-element branch chain
# speedup vs baseline: 1.0225x; 1.0084x over previous
.Lmask_slow:
	s_and_b64 vcc, exec, s[40:41]
	s_cbranch_vccnz .Lmask_k3
	s_nop 3
	v_mul_f32_e32 v108, 0x3e0293ee, v108
	v_mul_f32_e32 v109, 0x3e0293ee, v109
	v_mul_f32_e32 v111, 0x3e0293ee, v111
	v_mul_f32_e32 v105, 0x3e0293ee, v105
	v_mul_f32_e32 v110, 0x3e0293ee, v110
	v_mul_f32_e32 v104, 0x3e0293ee, v104
	v_mul_f32_e32 v106, 0x3e0293ee, v106
	v_mul_f32_e32 v107, 0x3e0293ee, v107
	v_mul_f32_e32 v100, 0x3e0293ee, v100
	v_mul_f32_e32 v102, 0x3e0293ee, v102
	v_mul_f32_e32 v96, 0x3e0293ee, v96
	v_mul_f32_e32 v98, 0x3e0293ee, v98
	v_mul_f32_e32 v101, 0x3e0293ee, v101
	v_mul_f32_e32 v103, 0x3e0293ee, v103
	v_mul_f32_e32 v97, 0x3e0293ee, v97
	v_mul_f32_e32 v99, 0x3e0293ee, v99
	v_or_b32_e32 v129, s91, v122
	v_or_b32_e32 v131, s91, v159
	v_sub_u32_e32 v129, v207, v129
	v_sub_u32_e32 v131, v207, v131
	v_cmp_lt_u32_e32 vcc, s63, v129
	v_cmp_lt_u32_e64 s[34:35], s63, v131
	s_nop 1
	v_cndmask_b32_e32 v108, v180, v108, vcc
	v_cndmask_b32_e64 v109, v180, v109, s[34:35]
	v_or_b32_e32 v129, s91, v161
	v_or_b32_e32 v131, s91, v163
	v_sub_u32_e32 v129, v207, v129
	v_sub_u32_e32 v131, v207, v131
	v_cmp_lt_u32_e32 vcc, s63, v129
	v_cmp_lt_u32_e64 s[34:35], s63, v131
	s_nop 1
	v_cndmask_b32_e32 v111, v180, v111, vcc
	v_cndmask_b32_e64 v105, v180, v105, s[34:35]
	v_or_b32_e32 v129, s91, v160
	v_or_b32_e32 v131, s91, v162
	v_sub_u32_e32 v129, v207, v129
	v_sub_u32_e32 v131, v207, v131
	v_cmp_lt_u32_e32 vcc, s63, v129
	v_cmp_lt_u32_e64 s[34:35], s63, v131
	s_nop 1
	v_cndmask_b32_e32 v110, v180, v110, vcc
	v_cndmask_b32_e64 v104, v180, v104, s[34:35]
	v_or_b32_e32 v129, s91, v164
	v_or_b32_e32 v131, s91, v165
	v_sub_u32_e32 v129, v207, v129
	v_sub_u32_e32 v131, v207, v131
	v_cmp_lt_u32_e32 vcc, s63, v129
	v_cmp_lt_u32_e64 s[34:35], s63, v131
	s_nop 1
	v_cndmask_b32_e32 v106, v180, v106, vcc
	v_cndmask_b32_e64 v107, v180, v107, s[34:35]
	v_or_b32_e32 v129, s91, v166
	v_or_b32_e32 v131, s91, v169
	v_sub_u32_e32 v129, v207, v129
	v_sub_u32_e32 v131, v207, v131
	v_cmp_lt_u32_e32 vcc, s63, v129
	v_cmp_lt_u32_e64 s[34:35], s63, v131
	s_nop 1
	v_cndmask_b32_e32 v100, v180, v100, vcc
	v_cndmask_b32_e64 v102, v180, v102, s[34:35]
	v_or_b32_e32 v129, s91, v188
	v_or_b32_e32 v131, s91, v192
	v_sub_u32_e32 v129, v207, v129
	v_sub_u32_e32 v131, v207, v131
	v_cmp_lt_u32_e32 vcc, s63, v129
	v_cmp_lt_u32_e64 s[34:35], s63, v131
	s_nop 1
	v_cndmask_b32_e32 v96, v180, v96, vcc
	v_cndmask_b32_e64 v98, v180, v98, s[34:35]
	v_or_b32_e32 v129, s91, v167
	v_or_b32_e32 v131, s91, v171
	v_sub_u32_e32 v129, v207, v129
	v_sub_u32_e32 v131, v207, v131
	v_cmp_lt_u32_e32 vcc, s63, v129
	v_cmp_lt_u32_e64 s[34:35], s63, v131
	s_nop 1
	v_cndmask_b32_e32 v101, v180, v101, vcc
	v_cndmask_b32_e64 v103, v180, v103, s[34:35]
	v_or_b32_e32 v129, s91, v190
	v_or_b32_e32 v131, s91, v194
	v_sub_u32_e32 v129, v207, v129
	v_sub_u32_e32 v131, v207, v131
	v_cmp_lt_u32_e32 vcc, s63, v129
	v_cmp_lt_u32_e64 s[34:35], s63, v131
	s_nop 1
	v_cndmask_b32_e32 v97, v180, v97, vcc
	v_cndmask_b32_e64 v99, v180, v99, s[34:35]
	s_branch .LBB0_370
.Lmask_k3:
	s_lshl_b32 s62, s92, 1
	s_add_i32 s62, s62, s82
	s_cmp_ge_i32 s62, s78
	s_cselect_b64 s[14:15], -1, 0
	s_cmp_lt_i32 s62, s86
	s_cselect_b64 s[34:35], -1, 0
	v_sub_u32_e32 v129, s62, v146
	s_and_b64 s[60:61], s[14:15], s[34:35]
	v_med3_i32 v129, v129, -7, 7
	s_movk_i32 s14, 0x7c
	v_mul_lo_u32 v129, v129, s14
	v_add_u32_e32 v129, 0x12000, v129
	s_and_b64 vcc, s[40:41], s[54:55]
	s_cbranch_vccz .Lrpb1_skip
	v_lshl_add_u32 v226, v208, 2, v129
	v_lshl_add_u32 v227, v209, 2, v129
	v_lshl_add_u32 v228, v212, 2, v129
	v_lshl_add_u32 v229, v214, 2, v129
	v_lshl_add_u32 v230, v210, 2, v129
	v_lshl_add_u32 v231, v213, 2, v129
	v_lshl_add_u32 v232, v215, 2, v129
	v_lshl_add_u32 v233, v216, 2, v129
	ds_read_b32 v226, v226 offset:928
	ds_read_b32 v227, v227 offset:928
	ds_read_b32 v228, v228 offset:928
	ds_read_b32 v229, v229 offset:928
	ds_read_b32 v230, v230 offset:928
	ds_read_b32 v231, v231 offset:928
	ds_read_b32 v232, v232 offset:928
	ds_read_b32 v233, v233 offset:928
	s_or_b32 s62, s62, 1
	s_cmp_ge_i32 s62, s78
	s_cselect_b64 s[34:35], -1, 0
	s_cmp_lt_i32 s62, s86
	s_cselect_b64 s[14:15], -1, 0
	v_sub_u32_e32 v129, s62, v146
	s_and_b64 s[14:15], s[34:35], s[14:15]
	v_med3_i32 v129, v129, -7, 7
	s_movk_i32 s34, 0x7c
	v_mul_lo_u32 v129, v129, s34
	v_add_u32_e32 v129, 0x12000, v129
	v_lshl_add_u32 v234, v208, 2, v129
	v_lshl_add_u32 v235, v218, 2, v129
	v_lshl_add_u32 v236, v220, 2, v129
	v_lshl_add_u32 v237, v222, 2, v129
	v_lshl_add_u32 v238, v217, 2, v129
	v_lshl_add_u32 v239, v219, 2, v129
	v_lshl_add_u32 v240, v221, 2, v129
	v_lshl_add_u32 v241, v223, 2, v129
	ds_read_b32 v234, v234 offset:928
	ds_read_b32 v235, v235 offset:928
	ds_read_b32 v236, v236 offset:928
	ds_read_b32 v237, v237 offset:928
	ds_read_b32 v238, v238 offset:928
	ds_read_b32 v239, v239 offset:928
	ds_read_b32 v240, v240 offset:928
	ds_read_b32 v241, v241 offset:928
	v_mul_f32_e32 v108, 0x3e0293ee, v108
	v_mul_f32_e32 v109, 0x3e0293ee, v109
	v_mul_f32_e32 v111, 0x3e0293ee, v111
	v_mul_f32_e32 v105, 0x3e0293ee, v105
	v_mul_f32_e32 v110, 0x3e0293ee, v110
	v_mul_f32_e32 v104, 0x3e0293ee, v104
	v_mul_f32_e32 v106, 0x3e0293ee, v106
	v_mul_f32_e32 v107, 0x3e0293ee, v107
	v_mul_f32_e32 v100, 0x3e0293ee, v100
	v_mul_f32_e32 v102, 0x3e0293ee, v102
	v_mul_f32_e32 v96, 0x3e0293ee, v96
	v_mul_f32_e32 v98, 0x3e0293ee, v98
	v_mul_f32_e32 v101, 0x3e0293ee, v101
	v_mul_f32_e32 v103, 0x3e0293ee, v103
	v_mul_f32_e32 v97, 0x3e0293ee, v97
	v_mul_f32_e32 v99, 0x3e0293ee, v99
	s_waitcnt lgkmcnt(0)
	s_and_b64 s[34:35], s[60:61], s[50:51]
	v_fmamk_f32 v131, v226, 0x3fb8aa3b, v108
	s_and_b64 vcc, s[34:35], s[52:53]
	v_cndmask_b32_e32 v108, v180, v131, vcc
	v_readlane_b32 s34, v254, 28
	v_readlane_b32 s35, v254, 29
	s_and_b64 s[34:35], s[60:61], s[34:35]
	v_readlane_b32 s92, v254, 30
	v_readlane_b32 s93, v254, 31
	v_fmamk_f32 v131, v227, 0x3fb8aa3b, v109
	s_and_b64 vcc, s[34:35], s[92:93]
	v_cndmask_b32_e32 v109, v180, v131, vcc
	v_readlane_b32 s34, v254, 36
	v_readlane_b32 s35, v254, 37
	s_and_b64 s[34:35], s[60:61], s[34:35]
	v_readlane_b32 s92, v254, 38
	v_readlane_b32 s93, v254, 39
	v_fmamk_f32 v131, v228, 0x3fb8aa3b, v111
	s_and_b64 vcc, s[34:35], s[92:93]
	v_cndmask_b32_e32 v111, v180, v131, vcc
	v_readlane_b32 s34, v254, 44
	v_readlane_b32 s35, v254, 45
	s_and_b64 s[34:35], s[60:61], s[34:35]
	v_readlane_b32 s92, v254, 46
	v_readlane_b32 s93, v254, 47
	v_fmamk_f32 v131, v229, 0x3fb8aa3b, v105
	s_and_b64 vcc, s[34:35], s[92:93]
	v_cndmask_b32_e32 v105, v180, v131, vcc
	v_readlane_b32 s34, v254, 32
	v_readlane_b32 s35, v254, 33
	s_and_b64 s[34:35], s[60:61], s[34:35]
	v_readlane_b32 s92, v254, 34
	v_readlane_b32 s93, v254, 35
	v_fmamk_f32 v131, v230, 0x3fb8aa3b, v110
	s_and_b64 vcc, s[34:35], s[92:93]
	v_cndmask_b32_e32 v110, v180, v131, vcc
	v_readlane_b32 s34, v254, 40
	v_readlane_b32 s35, v254, 41
	s_and_b64 s[34:35], s[60:61], s[34:35]
	v_readlane_b32 s92, v254, 42
	v_readlane_b32 s93, v254, 43
	v_fmamk_f32 v131, v231, 0x3fb8aa3b, v104
	s_and_b64 vcc, s[34:35], s[92:93]
	v_cndmask_b32_e32 v104, v180, v131, vcc
	v_readlane_b32 s34, v254, 48
	v_readlane_b32 s35, v254, 49
	s_and_b64 s[34:35], s[60:61], s[34:35]
	v_readlane_b32 s92, v254, 50
	v_readlane_b32 s93, v254, 51
	v_fmamk_f32 v131, v232, 0x3fb8aa3b, v106
	s_and_b64 vcc, s[34:35], s[92:93]
	v_cndmask_b32_e32 v106, v180, v131, vcc
	v_readlane_b32 s34, v254, 52
	v_readlane_b32 s35, v254, 53
	s_and_b64 s[34:35], s[60:61], s[34:35]
	v_readlane_b32 s60, v254, 54
	v_readlane_b32 s61, v254, 55
	v_fmamk_f32 v131, v233, 0x3fb8aa3b, v107
	s_and_b64 vcc, s[34:35], s[60:61]
	v_cndmask_b32_e32 v107, v180, v131, vcc
	s_and_b64 s[34:35], s[14:15], s[50:51]
	v_fmamk_f32 v131, v234, 0x3fb8aa3b, v100
	s_and_b64 vcc, s[34:35], s[52:53]
	v_cndmask_b32_e32 v100, v180, v131, vcc
	v_readlane_b32 s34, v254, 60
	v_readlane_b32 s35, v254, 61
	s_and_b64 s[34:35], s[14:15], s[34:35]
	v_readlane_b32 s92, v254, 62
	v_readlane_b32 s93, v254, 63
	v_fmamk_f32 v131, v235, 0x3fb8aa3b, v102
	s_and_b64 vcc, s[34:35], s[92:93]
	v_cndmask_b32_e32 v102, v180, v131, vcc
	s_and_b64 s[34:35], s[14:15], s[94:95]
	v_fmamk_f32 v131, v236, 0x3fb8aa3b, v96
	s_and_b64 vcc, s[34:35], s[96:97]
	v_cndmask_b32_e32 v96, v180, v131, vcc
	s_and_b64 s[34:35], s[14:15], s[4:5]
	v_fmamk_f32 v131, v237, 0x3fb8aa3b, v98
	s_and_b64 vcc, s[34:35], s[6:7]
	v_cndmask_b32_e32 v98, v180, v131, vcc
	v_readlane_b32 s34, v254, 56
	v_readlane_b32 s35, v254, 57
	s_and_b64 s[34:35], s[14:15], s[34:35]
	v_readlane_b32 s92, v254, 58
	v_readlane_b32 s93, v254, 59
	v_fmamk_f32 v131, v238, 0x3fb8aa3b, v101
	s_and_b64 vcc, s[34:35], s[92:93]
	v_cndmask_b32_e32 v101, v180, v131, vcc
	v_readlane_b32 s34, v255, 0
	v_readlane_b32 s35, v255, 1
	s_and_b64 s[34:35], s[14:15], s[34:35]
	v_readlane_b32 s92, v255, 2
	v_readlane_b32 s93, v255, 3
	v_fmamk_f32 v131, v239, 0x3fb8aa3b, v103
	s_and_b64 vcc, s[34:35], s[92:93]
	v_cndmask_b32_e32 v103, v180, v131, vcc
	s_and_b64 s[34:35], s[14:15], s[98:99]
	v_fmamk_f32 v131, v240, 0x3fb8aa3b, v97
	s_and_b64 vcc, s[34:35], s[0:1]
	v_cndmask_b32_e32 v97, v180, v131, vcc
	s_and_b64 s[34:35], s[14:15], s[8:9]
	v_fmamk_f32 v131, v241, 0x3fb8aa3b, v99
	s_and_b64 vcc, s[34:35], s[10:11]
	v_cndmask_b32_e32 v99, v180, v131, vcc
	s_branch .LBB0_370
